# phase-0 grid sync: L2 write-back only from the 73 workgroups that stored in phase 0
# speedup vs baseline: 1.0003x; 1.0003x over previous
.LBB0_1425:
	s_waitcnt vmcnt(0)
	s_barrier
	s_mov_b64 s[2:3], exec
	v_readlane_b32 s4, v254, 35
	v_readlane_b32 s5, v254, 36
	s_and_b64 s[4:5], s[2:3], s[4:5]
	s_mov_b64 exec, s[4:5]
	s_cbranch_execz .LBB0_1435
	v_readlane_b32 s4, v254, 1
	v_readlane_b32 s5, v254, 2
	v_readlane_b32 s6, v254, 0
	s_cmpk_gt_u32 s6, 72
	s_cbranch_scc1 .Lskip_cgwb
	buffer_wbl2 sc1
.Lskip_cgwb:
	s_load_dwordx2 s[4:5], s[4:5], 0x58
	s_mov_b64 s[6:7], exec
	v_mbcnt_lo_u32_b32 v1, s6, 0
	v_mbcnt_hi_u32_b32 v1, s7, v1
	v_cmp_eq_u32_e32 vcc, 0, v1
	s_waitcnt lgkmcnt(0)
	global_load_dword v0, v133, s[4:5] offset:40
	s_and_saveexec_b64 s[8:9], vcc
	s_cbranch_execz .LBB0_1428
	s_bcnt1_i32_b64 s6, s[6:7]
	v_mov_b32_e32 v2, s6
	global_atomic_add v2, v133, v2, s[4:5] offset:32 sc0
